# P5 norm_mod_bf: first row of the next iteration prefetched during the second row's block; GDN chain section D (T @ R): all operand reads issued before the first MFMA
# speedup vs baseline: 1.0174x; 1.0058x over previous
; #define LAS __attribute__((address_space(3)))
; __device__ __forceinline__ unsigned pk2(float lo, float hi) { const f32v2_t f = {lo, hi}; const bf16v2_t b = __builtin_convertvector(f, bf16v2_t); return __builtin_bit_cast(unsigned, b); }
; #define WAVE_SYNC() do { asm volatile("s_waitcnt lgkmcnt(0)" ::: "memory"); __builtin_amdgcn_wave_barrier(); asm volatile("" ::: "memory"); } while (0)
; #define MFMA16(a, b, c) __builtin_amdgcn_mfma_f32_16x16x32_bf16((a), (b), (c), 0, 0, 0)
; template <int MODE>
; __device__ NOINL void chain_item(const LAS Params* lp, int l, int item, bool ctx_out, LAS unsigned char* lds) {
;     ...
;         for (int dk = 0; dk < NDK; ++dk) { u32x2 pk; pk.x = pk2(Sacc[dk][0], Sacc[dk][1]); pk.y = pk2(Sacc[dk][2], Sacc[dk][3]); *(LAS u32x2*)(ST + fr * 136 + 16 * dk + 4 * fq) = pk; }
;         WAVE_SYNC();
;         f32x4 qs[4], ksm[4];
; #pragma unroll
;         for (int ct = 0; ct < 4; ++ct) { qs[ct] = (f32x4){0.f, 0.f, 0.f, 0.f}; ksm[ct] = (f32x4){0.f, 0.f, 0.f, 0.f}; }
; #pragma unroll
;         for (int ks = 0; ks < NKS; ++ks) {
;             const bf16x8 Bf = *(const LAS bf16x8*)(ST + fr * 136 + ks * 32 + fq * 8);
; #pragma unroll
;             for (int ct = 0; ct < 4; ++ct) {
;                 const bf16x8 Aq = *(const LAS bf16x8*)(Qs + (16 * ct + fr) * 136 + kcol + ks * 32 + fq * 8);
;                 qs[ct] = MFMA16(Aq, Bf, qs[ct]);
;                 if (MODE == 0) { const bf16x8 Ak = *(const LAS bf16x8*)(Ks + (16 * ct + fr) * 136 + ks * 32 + fq * 8); ksm[ct] = MFMA16(Ak, Bf, ksm[ct]); }
;             }
;         }
.LBB0_1141:
	s_or_b64 exec, exec, s[62:63]
	ds_write_b16 v178, v68
	v_cvt_pk_bf16_f32 v68, v28, v29
	v_cvt_pk_bf16_f32 v69, v30, v31
	v_cvt_pk_bf16_f32 v70, v40, v41
	v_cvt_pk_bf16_f32 v71, v42, v43
	ds_write2_b64 v113, v[68:69], v[70:71] offset1:4
	v_cvt_pk_bf16_f32 v68, v32, v33
	v_cvt_pk_bf16_f32 v69, v34, v35
	v_cvt_pk_bf16_f32 v70, v36, v37
	v_cvt_pk_bf16_f32 v71, v38, v39
	ds_write2_b64 v113, v[68:69], v[70:71] offset0:8 offset1:12
	v_cvt_pk_bf16_f32 v68, v56, v57
	v_cvt_pk_bf16_f32 v69, v58, v59
	v_cvt_pk_bf16_f32 v70, v52, v53
	v_cvt_pk_bf16_f32 v71, v54, v55
	ds_write2_b64 v113, v[68:69], v[70:71] offset0:16 offset1:20
	v_cvt_pk_bf16_f32 v68, v44, v45
	v_cvt_pk_bf16_f32 v69, v46, v47
	v_cvt_pk_bf16_f32 v70, v48, v49
	v_cvt_pk_bf16_f32 v71, v50, v51
	ds_write2_b64 v113, v[68:69], v[70:71] offset0:24 offset1:28
	s_waitcnt lgkmcnt(0)
	v_add_u32_e32 v119, v113, v154
	ds_read_b128 v[84:87], v119
	ds_read_b128 v[100:103], v179
	ds_read_b128 v[104:107], v179 offset:17408
	ds_read_b128 v[194:197], v179 offset:4352
	ds_read_b128 v[236:239], v179 offset:21760
	ds_read_b128 v[240:243], v179 offset:8704
	ds_read_b128 v[244:247], v179 offset:26112
	ds_read_b128 v[248:251], v179 offset:13056
	v_add_u32_e32 v121, 0x25500, v110
	s_waitcnt lgkmcnt(6)
	v_mfma_f32_16x16x32_bf16 v[96:99], v[100:103], v[84:87], 0
	ds_read_b128 v[100:103], v179 offset:30464
	ds_read_b128 v[88:91], v119 offset:64
	s_add_i32 s5, s4, 4
	s_waitcnt lgkmcnt(7)
	v_mfma_f32_16x16x32_bf16 v[198:201], v[104:107], v[84:87], 0
	ds_read_b128 v[104:107], v179 offset:64
	s_and_b64 s[20:21], vcc, exec
	s_waitcnt lgkmcnt(7)
	v_mfma_f32_16x16x32_bf16 v[92:95], v[194:197], v[84:87], 0
	ds_read_b128 v[194:197], v179 offset:17472
	s_cselect_b32 s5, s1, s5
	s_waitcnt lgkmcnt(7)
	v_mfma_f32_16x16x32_bf16 v[232:235], v[236:239], v[84:87], 0
	ds_read_b128 v[236:239], v179 offset:4416
	s_add_i32 s22, s4, 40
	s_waitcnt lgkmcnt(7)
	v_mfma_f32_16x16x32_bf16 v[80:83], v[240:243], v[84:87], 0
	ds_read_b128 v[240:243], v179 offset:21824
	s_and_b64 s[20:21], vcc, exec
	s_waitcnt lgkmcnt(7)
	v_mfma_f32_16x16x32_bf16 v[72:75], v[244:247], v[84:87], 0
	ds_read_b128 v[244:247], v179 offset:8768
	s_cselect_b32 s20, s1, s22
	s_waitcnt lgkmcnt(7)
	v_mfma_f32_16x16x32_bf16 v[76:79], v[248:251], v[84:87], 0
	ds_read_b128 v[248:251], v179 offset:26176
	s_cmp_lt_u32 s1, 4
	s_waitcnt lgkmcnt(7)
	v_mfma_f32_16x16x32_bf16 v[68:71], v[100:103], v[84:87], 0
	ds_read_b128 v[100:103], v179 offset:13120
	s_cselect_b32 s1, s5, s20
	s_waitcnt lgkmcnt(6)
	v_mfma_f32_16x16x32_bf16 v[96:99], v[104:107], v[88:91], v[96:99]
	ds_read_b128 v[104:107], v179 offset:30528
	ds_read_b128 v[84:87], v119 offset:128
	s_lshl_b32 s5, s1, 6
	s_waitcnt lgkmcnt(7)
	v_mfma_f32_16x16x32_bf16 v[198:201], v[194:197], v[88:91], v[198:201]
	ds_read_b128 v[194:197], v179 offset:128
	s_add_i32 s20, s18, s5
	s_waitcnt lgkmcnt(7)
	v_mfma_f32_16x16x32_bf16 v[92:95], v[236:239], v[88:91], v[92:95]
	ds_read_b128 v[236:239], v179 offset:17536
	s_or_b32 s5, s5, s38
	s_waitcnt lgkmcnt(7)
	v_mfma_f32_16x16x32_bf16 v[232:235], v[240:243], v[88:91], v[232:235]
	ds_read_b128 v[240:243], v179 offset:4480
	s_cmp_lt_u32 s1, 4
	s_waitcnt lgkmcnt(7)
	v_mfma_f32_16x16x32_bf16 v[80:83], v[244:247], v[88:91], v[80:83]
	ds_read_b128 v[244:247], v179 offset:21888
	s_cselect_b32 s1, s5, s20
	s_waitcnt lgkmcnt(7)
	v_mfma_f32_16x16x32_bf16 v[72:75], v[248:251], v[88:91], v[72:75]
	ds_read_b128 v[248:251], v179 offset:8832
	s_mul_hi_i32 s21, s1, s19
	s_waitcnt lgkmcnt(7)
	v_mfma_f32_16x16x32_bf16 v[76:79], v[100:103], v[88:91], v[76:79]
	ds_read_b128 v[100:103], v179 offset:26240
	s_mul_i32 s20, s1, s19
	s_waitcnt lgkmcnt(7)
	v_mfma_f32_16x16x32_bf16 v[68:71], v[104:107], v[88:91], v[68:71]
	ds_read_b128 v[104:107], v179 offset:13184
	v_mov_b32_e32 v123, v1
	s_waitcnt lgkmcnt(6)
	v_mfma_f32_16x16x32_bf16 v[96:99], v[194:197], v[84:87], v[96:99]
	ds_read_b128 v[194:197], v179 offset:30592
	ds_read_b128 v[88:91], v119 offset:192
	v_add_u32_e32 v119, s34, v155
	v_mov_b32_e32 v125, v1
	s_waitcnt lgkmcnt(7)
	v_mfma_f32_16x16x32_bf16 v[198:201], v[236:239], v[84:87], v[198:201]
	ds_read_b128 v[236:239], v179 offset:192
	v_mov_b32_e32 v127, v1
	s_waitcnt lgkmcnt(7)
	v_mfma_f32_16x16x32_bf16 v[92:95], v[240:243], v[84:87], v[92:95]
	ds_read_b128 v[240:243], v179 offset:17600
	v_mov_b32_e32 v129, v1
	s_waitcnt lgkmcnt(7)
	v_mfma_f32_16x16x32_bf16 v[232:235], v[244:247], v[84:87], v[232:235]
	ds_read_b128 v[244:247], v179 offset:4544
	v_mov_b32_e32 v131, v1
	s_waitcnt lgkmcnt(7)
	v_mfma_f32_16x16x32_bf16 v[80:83], v[248:251], v[84:87], v[80:83]
	ds_read_b128 v[248:251], v179 offset:21952
	v_mov_b32_e32 v133, v1
	s_waitcnt lgkmcnt(7)
	v_mfma_f32_16x16x32_bf16 v[72:75], v[100:103], v[84:87], v[72:75]
	ds_read_b128 v[100:103], v179 offset:8896
	v_mov_b32_e32 v135, v1
	s_waitcnt lgkmcnt(7)
	v_mfma_f32_16x16x32_bf16 v[76:79], v[104:107], v[84:87], v[76:79]
	ds_read_b128 v[104:107], v179 offset:26304
	v_mov_b32_e32 v137, v1
	s_waitcnt lgkmcnt(7)
	v_mfma_f32_16x16x32_bf16 v[68:71], v[194:197], v[84:87], v[68:71]
	ds_read_b128 v[194:197], v179 offset:13248
	v_mov_b32_e32 v139, v1
	s_waitcnt lgkmcnt(6)
	v_mfma_f32_16x16x32_bf16 v[96:99], v[236:239], v[88:91], v[96:99]
	ds_read_b128 v[236:239], v179 offset:30656
	v_mov_b32_e32 v141, v1
	s_waitcnt lgkmcnt(6)
	v_mfma_f32_16x16x32_bf16 v[198:201], v[240:243], v[88:91], v[198:201]
	v_mov_b32_e32 v143, v1
	s_waitcnt lgkmcnt(5)
	v_mfma_f32_16x16x32_bf16 v[92:95], v[244:247], v[88:91], v[92:95]
	v_mov_b32_e32 v145, v1
	s_waitcnt lgkmcnt(4)
	v_mfma_f32_16x16x32_bf16 v[232:235], v[248:251], v[88:91], v[232:235]
	v_mov_b32_e32 v147, v1
	s_waitcnt lgkmcnt(3)
; #define LAS __attribute__((address_space(3)))
; __device__ __forceinline__ unsigned pk2(float lo, float hi) { const f32v2_t f = {lo, hi}; const bf16v2_t b = __builtin_convertvector(f, bf16v2_t); return __builtin_bit_cast(unsigned, b); }
; __device__ __forceinline__ float bflo(unsigned u) { return __uint_as_float(u << 16); }
; __device__ __forceinline__ float bfhi(unsigned u) { return __uint_as_float(u & 0xFFFF0000u); }
; template <int MODE>
; __device__ NOINL void chain_item(const LAS Params* lp, int l, int item, bool ctx_out, LAS unsigned char* lds) {
;     ...
;         float eg[4][4];
; #pragma unroll
;         for (int ct = 0; ct < 4; ++ct)
; #pragma unroll
;             for (int j = 0; j < 4; ++j) { const int c = 16 * ct + 4 * fq + j; eg[ct][j] = MODE == 0 ? gcs[128 + c] : __expf((float)(c + 1) * lg); }
;         bf16x8 Bv[2];
;         if (MODE == 0) {
; #pragma unroll
;             for (int ct = 0; ct < 4; ++ct) {
;                 const u32x2 vv = *(const LAS u32x2*)(VT + (dvrow + fr) * 72 + (((2 * ct + (fq >> 1)) ^ vkey) << 3) + 4 * (fq & 1));
;                 const float v4[4] = {bflo(vv.x), bfhi(vv.x), bflo(vv.y), bfhi(vv.y)};
;                 float r[4];
; #pragma unroll
;                 for (int j = 0; j < 4; ++j) r[j] = bts[16 * ct + 4 * fq + j] * (v4[j] - eg[ct][j] * ksm[ct][j]);
;                 u32x2 pk; pk.x = pk2(r[0], r[1]); pk.y = pk2(r[2], r[3]);
;                 *(LAS u32x2*)(RP + fr * 72 + 16 * ct + 4 * fq) = pk;
;             }
;             WAVE_SYNC();
;             bf16x8 Br[2];
;             Br[0] = *(const LAS bf16x8*)(RP + fr * 72 + fq * 8); Br[1] = *(const LAS bf16x8*)(RP + fr * 72 + 32 + fq * 8);
;             f32x4 vn[4];
; #pragma unroll
;             for (int ct = 0; ct < 4; ++ct) {
;                 vn[ct] = (f32x4){0.f, 0.f, 0.f, 0.f};
; #pragma unroll
;                 for (int ks = 0; ks < 2; ++ks) { const bf16x8 A = *(const LAS bf16x8*)(TT + (16 * ct + fr) * 72 + ks * 32 + fq * 8); vn[ct] = MFMA16(A, Br[ks], vn[ct]); }
;             }
;             WAVE_SYNC();
; #pragma unroll
;             for (int ct = 0; ct < 4; ++ct) { u32x2 pk; pk.x = pk2(vn[ct][0], vn[ct][1]); pk.y = pk2(vn[ct][2], vn[ct][3]); *(LAS u32x2*)(RP + fr * 72 + 16 * ct + 4 * fq) = pk; }
;             WAVE_SYNC();
;             Bv[0] = *(const LAS bf16x8*)(RP + fr * 72 + fq * 8); Bv[1] = *(const LAS bf16x8*)(RP + fr * 72 + 32 + fq * 8);
	v_mfma_f32_16x16x32_bf16 v[80:83], v[100:103], v[88:91], v[80:83]
	s_add_i32 s4, s4, -1
	s_waitcnt lgkmcnt(2)
	v_mfma_f32_16x16x32_bf16 v[72:75], v[104:107], v[88:91], v[72:75]
	s_cmp_lg_u32 s0, 36
	s_waitcnt lgkmcnt(1)
	v_mfma_f32_16x16x32_bf16 v[76:79], v[194:197], v[88:91], v[76:79]
	s_mov_b32 s1, s0
	s_waitcnt lgkmcnt(0)
	v_mfma_f32_16x16x32_bf16 v[68:71], v[236:239], v[88:91], v[68:71]
	ds_read_b64 v[88:89], v186 offset:53248
	ds_read_b128 v[104:107], v119 offset:512
	ds_read_b128 v[84:87], v121
	s_waitcnt lgkmcnt(2)
	v_lshlrev_b32_e32 v90, 16, v88
	v_and_b32_e32 v91, 0xffff0000, v88
	v_lshlrev_b32_e32 v88, 16, v89
	v_and_b32_e32 v89, 0xffff0000, v89
	s_waitcnt lgkmcnt(1)
	v_pk_fma_f32 v[90:91], v[198:199], v[104:105], v[90:91] neg_lo:[1,0,0] neg_hi:[1,0,0]
	v_pk_fma_f32 v[88:89], v[200:201], v[106:107], v[88:89] neg_lo:[1,0,0] neg_hi:[1,0,0]
	s_waitcnt lgkmcnt(0)
	v_pk_mul_f32 v[84:85], v[84:85], v[90:91]
	v_pk_mul_f32 v[86:87], v[86:87], v[88:89]
	v_cvt_pk_bf16_f32 v148, v84, v85
	v_cvt_pk_bf16_f32 v149, v86, v87
	ds_read_b128 v[100:103], v119 offset:576
	ds_read_b128 v[88:91], v119 offset:640
	ds_read_b128 v[84:87], v119 offset:704
	ds_write_b64 v158, v[148:149] offset:4352
	ds_read_b64 v[148:149], v187 offset:53248
	ds_read_b128 v[194:197], v121 offset:64
	v_add_u32_e32 v119, v158, v154
	s_waitcnt lgkmcnt(1)
	v_lshlrev_b32_e32 v198, 16, v148
	v_and_b32_e32 v199, 0xffff0000, v148
	v_lshlrev_b32_e32 v148, 16, v149
	v_and_b32_e32 v149, 0xffff0000, v149
	v_pk_fma_f32 v[198:199], v[232:233], v[100:101], v[198:199] neg_lo:[1,0,0] neg_hi:[1,0,0]
	v_pk_fma_f32 v[148:149], v[234:235], v[102:103], v[148:149] neg_lo:[1,0,0] neg_hi:[1,0,0]
	s_waitcnt lgkmcnt(0)
	v_pk_mul_f32 v[194:195], v[194:195], v[198:199]
	v_pk_mul_f32 v[148:149], v[196:197], v[148:149]
	v_cvt_pk_bf16_f32 v194, v194, v195
	v_cvt_pk_bf16_f32 v195, v148, v149
	ds_write_b64 v158, v[194:195] offset:4384
	ds_read_b64 v[148:149], v188 offset:53248
	ds_read_b128 v[194:197], v121 offset:128
	s_waitcnt lgkmcnt(1)
	v_lshlrev_b32_e32 v198, 16, v148
	v_and_b32_e32 v199, 0xffff0000, v148
	v_lshlrev_b32_e32 v148, 16, v149
	v_and_b32_e32 v149, 0xffff0000, v149
	v_pk_fma_f32 v[72:73], v[72:73], v[88:89], v[198:199] neg_lo:[1,0,0] neg_hi:[1,0,0]
	v_pk_fma_f32 v[74:75], v[74:75], v[90:91], v[148:149] neg_lo:[1,0,0] neg_hi:[1,0,0]
	s_waitcnt lgkmcnt(0)
	v_pk_mul_f32 v[72:73], v[194:195], v[72:73]
	v_pk_mul_f32 v[74:75], v[196:197], v[74:75]
	v_cvt_pk_bf16_f32 v72, v72, v73
	v_cvt_pk_bf16_f32 v73, v74, v75
	ds_write_b64 v158, v[72:73] offset:4416
	ds_read_b64 v[72:73], v189 offset:53248
	s_waitcnt lgkmcnt(0)
	v_lshlrev_b32_e32 v148, 16, v72
	v_and_b32_e32 v149, 0xffff0000, v72
	v_lshlrev_b32_e32 v194, 16, v73
	v_and_b32_e32 v195, 0xffff0000, v73
	ds_read_b128 v[72:75], v121 offset:192
	v_pk_fma_f32 v[68:69], v[68:69], v[84:85], v[148:149] neg_lo:[1,0,0] neg_hi:[1,0,0]
	v_pk_fma_f32 v[70:71], v[70:71], v[86:87], v[194:195] neg_lo:[1,0,0] neg_hi:[1,0,0]
	v_add_u32_e32 v121, v159, v157
	v_lshl_add_u64 v[148:149], s[20:21], 1, v[116:117]
	s_waitcnt lgkmcnt(0)
	v_pk_mul_f32 v[68:69], v[72:73], v[68:69]
	v_pk_mul_f32 v[70:71], v[74:75], v[70:71]
	v_cvt_pk_bf16_f32 v68, v68, v69
	v_cvt_pk_bf16_f32 v69, v70, v71
	ds_write_b64 v158, v[68:69] offset:4448
	s_waitcnt lgkmcnt(0)
	ds_read_b128 v[68:71], v119 offset:4352
	ds_read_b128 v[72:75], v119 offset:4416
	ds_read_b128 v[194:197], v121
	ds_read_b128 v[198:201], v121 offset:64
	v_add_u32_e32 v121, v159, v180
	ds_read_b128 v[232:235], v121
	ds_read_b128 v[236:239], v121 offset:64
	ds_read_b128 v[240:243], v121 offset:2304
	ds_read_b128 v[244:247], v121 offset:2368
	ds_read_b128 v[248:251], v121 offset:4608
	s_waitcnt lgkmcnt(6)
	v_mfma_f32_16x16x32_bf16 v[194:197], v[194:197], v[68:71], 0
	s_waitcnt lgkmcnt(5)
	v_mfma_f32_16x16x32_bf16 v[194:197], v[198:201], v[72:75], v[194:197]
	ds_read_b128 v[198:201], v121 offset:4672
	v_add_u32_e32 v121, 0x1000, v158
	s_waitcnt lgkmcnt(5)
	v_mfma_f32_16x16x32_bf16 v[232:235], v[232:235], v[68:71], 0
	s_waitcnt lgkmcnt(4)
	v_mfma_f32_16x16x32_bf16 v[232:235], v[236:239], v[72:75], v[232:235]
	s_waitcnt lgkmcnt(3)
	v_mfma_f32_16x16x32_bf16 v[240:243], v[240:243], v[68:71], 0
	s_waitcnt lgkmcnt(2)
	v_mfma_f32_16x16x32_bf16 v[240:243], v[244:247], v[72:75], v[240:243]
	s_waitcnt lgkmcnt(1)
	v_mfma_f32_16x16x32_bf16 v[248:251], v[248:251], v[68:71], 0
	s_waitcnt lgkmcnt(0)
	v_mfma_f32_16x16x32_bf16 v[248:251], v[198:201], v[72:75], v[248:251]
	v_cvt_pk_bf16_f32 v72, v194, v195
	v_cvt_pk_bf16_f32 v73, v196, v197
	v_cvt_pk_bf16_f32 v74, v232, v233
	v_cvt_pk_bf16_f32 v75, v234, v235
	ds_write2_b64 v121, v[72:73], v[74:75] offset0:32 offset1:36
	v_cvt_pk_bf16_f32 v72, v240, v241
	v_cvt_pk_bf16_f32 v73, v242, v243
	s_nop 1
	v_cvt_pk_bf16_f32 v68, v248, v249
	v_cvt_pk_bf16_f32 v69, v250, v251
	ds_write2_b64 v121, v[72:73], v[68:69] offset0:40 offset1:44
	s_waitcnt lgkmcnt(0)
	s_barrier
; #define LAS __attribute__((address_space(3)))
; __device__ __forceinline__ bf16_t f2bf(float f) { return (bf16_t)(pk2(f, f) & 0xFFFFu); }
; #define MFMA16(a, b, c) __builtin_amdgcn_mfma_f32_16x16x32_bf16((a), (b), (c), 0, 0, 0)
; template <int MODE>
; __device__ NOINL void chain_item(const LAS Params* lp, int l, int item, bool ctx_out, LAS unsigned char* lds) {
;     ...
;             Bv[0] = *(const LAS bf16x8*)(RP + fr * 72 + fq * 8); Bv[1] = *(const LAS bf16x8*)(RP + fr * 72 + 32 + fq * 8);
;         } else {
;             Bv[0] = *(const LAS bf16x8*)(VT + (dvrow + fr) * 72 + ((fq ^ vkey) << 3)); Bv[1] = *(const LAS bf16x8*)(VT + (dvrow + fr) * 72 + (((4 + fq) ^ vkey) << 3));
;         }
;         {
;             typedef __attribute__((address_space(1))) bf16_t gbf16;
;             bf16_t* ob; int ldo;
;             if (MODE == 0) { if (dir == 0) { ob = p.hbuf + 256 + h * 128 + 16 * w; ldo = 1024; } else { ob = p.hyproj + h * 128 + 16 * w; ldo = 768; } }
;             else { if (dir == 0) { ob = p.hbuf + 768 + (h + hh) * 64 + 16 * (w & 3); ldo = 1024; } else { ob = p.hyproj + 512 + (h + hh) * 64 + 16 * (w & 3); ldo = 768; } }
; #pragma unroll
;             for (int ct = 0; ct < 4; ++ct) {
;                 f32x4 acc = {0.f, 0.f, 0.f, 0.f};
; #pragma unroll
;                 for (int ks = 0; ks < 2; ++ks) { const bf16x8 A = *(const LAS bf16x8*)(AT + hh * 4608 + (16 * ct + fr) * 72 + ks * 32 + fq * 8); acc = MFMA16(A, Bv[ks], acc); }
;                 gbf16* og = (gbf16*)ob + (size_t)row0 * ldo + fr;
; #pragma unroll
;                 for (int j = 0; j < 4; ++j) { const int c = 16 * ct + 4 * fq + j, tok = dir ? 63 - c : c; og[tok * ldo] = f2bf(eg[ct][j] * qs[ct][j] + acc[j]); }
;             }
;         }
;         {
;             const float gl = MODE == 0 ? gcs[128 + 63] : __expf(64.f * lg);
; #pragma unroll
;             for (int dk = 0; dk < NDK; ++dk) {
;                 Sacc[dk] = Sacc[dk] * gl;
; #pragma unroll
;                 for (int ks = 0; ks < 2; ++ks) { const bf16x8 A = *(const LAS bf16x8*)(KT + (kcol + 16 * dk + fr) * 72 + (((ks * 4 + fq) ^ (((kcol >> 4) + dk) & 7)) << 3)); Sacc[dk] = MFMA16(A, Bv[ks], Sacc[dk]); }
	ds_read_b128 v[72:75], v119 offset:4352
	ds_read_b128 v[68:71], v119 offset:4416
	v_add_u32_e32 v218, v160, v157
	v_add_u32_e32 v219, v160, v180
	v_mov_b32_e32 v119, v1
	v_mov_b32_e32 v121, v1
	ds_read_b128 v[194:197], v218
	ds_read_b128 v[232:235], v219
	ds_read_b128 v[244:247], v219 offset:2304
	ds_read_b128 v[236:239], v219 offset:4608
	ds_read_b128 v[198:201], v218 offset:64
	ds_read_b128 v[240:243], v219 offset:64
	ds_read_b128 v[248:251], v219 offset:2368
	s_waitcnt lgkmcnt(6)
	v_mfma_f32_16x16x32_bf16 v[194:197], v[194:197], v[72:75], 0
	s_waitcnt lgkmcnt(5)
	v_mfma_f32_16x16x32_bf16 v[232:235], v[232:235], v[72:75], 0
	s_waitcnt lgkmcnt(4)
	v_mfma_f32_16x16x32_bf16 v[244:247], v[244:247], v[72:75], 0
	s_waitcnt lgkmcnt(3)
	v_mfma_f32_16x16x32_bf16 v[236:239], v[236:239], v[72:75], 0
	s_waitcnt lgkmcnt(2)
	v_mfma_f32_16x16x32_bf16 v[194:197], v[198:201], v[68:71], v[194:197]
	ds_read_b128 v[198:201], v219 offset:4672
	s_waitcnt lgkmcnt(2)
	v_mfma_f32_16x16x32_bf16 v[232:235], v[240:243], v[68:71], v[232:235]
	s_waitcnt lgkmcnt(1)
	v_mfma_f32_16x16x32_bf16 v[244:247], v[248:251], v[68:71], v[244:247]
	s_waitcnt lgkmcnt(0)
	v_mfma_f32_16x16x32_bf16 v[236:239], v[198:201], v[68:71], v[236:239]
	v_lshl_add_u64 v[240:241], v[148:149], 0, v[0:1]
	v_lshl_add_u64 v[242:243], v[148:149], 0, v[118:119]
	v_lshl_add_u64 v[248:249], v[148:149], 0, v[120:121]
	v_lshl_add_u64 v[250:251], v[148:149], 0, v[122:123]
	s_nop 3
	v_fma_f32 v194, v96, v104, v194
	v_fma_f32 v195, v97, v105, v195
	v_fma_f32 v196, v98, v106, v196
	v_fma_f32 v197, v99, v107, v197
	v_cvt_pk_bf16_f32 v194, v194, v194
	v_cvt_pk_bf16_f32 v195, v195, v195
	v_cvt_pk_bf16_f32 v196, v196, v196
	v_cvt_pk_bf16_f32 v197, v197, v197
	global_store_short v[240:241], v194, off
	global_store_short v[242:243], v195, off
	global_store_short v[248:249], v196, off
	global_store_short v[250:251], v197, off
	v_lshl_add_u64 v[240:241], v[148:149], 0, v[124:125]
	v_lshl_add_u64 v[242:243], v[148:149], 0, v[126:127]
	v_lshl_add_u64 v[248:249], v[148:149], 0, v[128:129]
	v_lshl_add_u64 v[250:251], v[148:149], 0, v[130:131]
	v_fma_f32 v232, v92, v100, v232
	v_fma_f32 v233, v93, v101, v233
	v_fma_f32 v234, v94, v102, v234
	v_fma_f32 v235, v95, v103, v235
	v_cvt_pk_bf16_f32 v232, v232, v232
	v_cvt_pk_bf16_f32 v233, v233, v233
	v_cvt_pk_bf16_f32 v234, v234, v234
	v_cvt_pk_bf16_f32 v235, v235, v235
	global_store_short v[240:241], v232, off
	global_store_short v[242:243], v233, off
	global_store_short v[248:249], v234, off
	global_store_short v[250:251], v235, off
	v_lshl_add_u64 v[240:241], v[148:149], 0, v[132:133]
	v_lshl_add_u64 v[242:243], v[148:149], 0, v[134:135]
	v_lshl_add_u64 v[248:249], v[148:149], 0, v[136:137]
	v_lshl_add_u64 v[250:251], v[148:149], 0, v[138:139]
	v_fma_f32 v244, v80, v88, v244
	v_fma_f32 v245, v81, v89, v245
	v_fma_f32 v246, v82, v90, v246
	v_fma_f32 v247, v83, v91, v247
	v_cvt_pk_bf16_f32 v244, v244, v244
	v_cvt_pk_bf16_f32 v245, v245, v245
	v_cvt_pk_bf16_f32 v246, v246, v246
	v_cvt_pk_bf16_f32 v247, v247, v247
	global_store_short v[240:241], v244, off
	global_store_short v[242:243], v245, off
	global_store_short v[248:249], v246, off
	global_store_short v[250:251], v247, off
	v_lshl_add_u64 v[240:241], v[148:149], 0, v[140:141]
	v_lshl_add_u64 v[242:243], v[148:149], 0, v[142:143]
	v_lshl_add_u64 v[248:249], v[148:149], 0, v[144:145]
	v_lshl_add_u64 v[250:251], v[148:149], 0, v[146:147]
	v_fma_f32 v236, v76, v84, v236
	v_fma_f32 v237, v77, v85, v237
	v_fma_f32 v238, v78, v86, v238
	v_fma_f32 v239, v79, v87, v239
	v_cvt_pk_bf16_f32 v236, v236, v236
	v_cvt_pk_bf16_f32 v237, v237, v237
	v_cvt_pk_bf16_f32 v238, v238, v238
	v_cvt_pk_bf16_f32 v239, v239, v239
	global_store_short v[240:241], v236, off
	global_store_short v[242:243], v237, off
	global_store_short v[248:249], v238, off
	global_store_short v[250:251], v239, off
	v_mov_b32_e32 v76, s17
	ds_read_b32 v76, v76
	v_add_u32_e32 v83, v161, v155
	v_add_u32_e32 v82, v181, v182
	v_add_u32_e32 v84, v161, v182
	v_add_u32_e32 v85, v161, v183
	v_add_u32_e32 v86, v161, v162
	ds_read_b128 v[88:91], v83 offset:34816
	ds_read_b128 v[92:95], v82 offset:34816
	ds_read_b128 v[96:99], v190 offset:34816
	ds_read_b128 v[100:103], v191 offset:34816
	ds_read_b128 v[104:107], v83 offset:44096
	ds_read_b128 v[194:197], v84 offset:46400
	ds_read_b128 v[198:201], v85 offset:48704
	ds_read_b128 v[232:235], v86 offset:51008
	s_waitcnt lgkmcnt(8)
; #define LAS __attribute__((address_space(3)))
; #define MFMA16(a, b, c) __builtin_amdgcn_mfma_f32_16x16x32_bf16((a), (b), (c), 0, 0, 0)
; template <int MODE>
; __device__ NOINL void chain_item(const LAS Params* lp, int l, int item, bool ctx_out, LAS unsigned char* lds) {
;     ...
;         {
;             const float gl = MODE == 0 ? gcs[128 + 63] : __expf(64.f * lg);
; #pragma unroll
;             for (int dk = 0; dk < NDK; ++dk) {
;                 Sacc[dk] = Sacc[dk] * gl;
; #pragma unroll
;                 for (int ks = 0; ks < 2; ++ks) { const bf16x8 A = *(const LAS bf16x8*)(KT + (kcol + 16 * dk + fr) * 72 + (((ks * 4 + fq) ^ (((kcol >> 4) + dk) & 7)) << 3)); Sacc[dk] = MFMA16(A, Bv[ks], Sacc[dk]); }
;             }
;         }
;     }
	v_pk_mul_f32 v[30:31], v[30:31], v[76:77] op_sel_hi:[1,0]
	v_pk_mul_f32 v[28:29], v[28:29], v[76:77] op_sel_hi:[1,0]
	v_pk_mul_f32 v[42:43], v[42:43], v[76:77] op_sel_hi:[1,0]
	v_pk_mul_f32 v[40:41], v[40:41], v[76:77] op_sel_hi:[1,0]
	v_pk_mul_f32 v[34:35], v[34:35], v[76:77] op_sel_hi:[1,0]
	v_pk_mul_f32 v[32:33], v[32:33], v[76:77] op_sel_hi:[1,0]
	v_pk_mul_f32 v[38:39], v[38:39], v[76:77] op_sel_hi:[1,0]
	v_pk_mul_f32 v[36:37], v[36:37], v[76:77] op_sel_hi:[1,0]
	v_pk_mul_f32 v[58:59], v[58:59], v[76:77] op_sel_hi:[1,0]
	v_pk_mul_f32 v[56:57], v[56:57], v[76:77] op_sel_hi:[1,0]
	v_pk_mul_f32 v[54:55], v[54:55], v[76:77] op_sel_hi:[1,0]
	v_pk_mul_f32 v[52:53], v[52:53], v[76:77] op_sel_hi:[1,0]
	v_pk_mul_f32 v[46:47], v[46:47], v[76:77] op_sel_hi:[1,0]
	v_pk_mul_f32 v[44:45], v[44:45], v[76:77] op_sel_hi:[1,0]
	v_pk_mul_f32 v[50:51], v[50:51], v[76:77] op_sel_hi:[1,0]
	v_pk_mul_f32 v[48:49], v[48:49], v[76:77] op_sel_hi:[1,0]
	s_waitcnt lgkmcnt(7)
	v_mfma_f32_16x16x32_bf16 v[28:31], v[88:91], v[72:75], v[28:31]
	ds_read_b128 v[88:91], v83 offset:34880
	s_waitcnt lgkmcnt(7)
	v_mfma_f32_16x16x32_bf16 v[40:43], v[92:95], v[72:75], v[40:43]
	ds_read_b128 v[92:95], v82 offset:34880
	s_waitcnt lgkmcnt(7)
	v_mfma_f32_16x16x32_bf16 v[32:35], v[96:99], v[72:75], v[32:35]
	ds_read_b128 v[96:99], v190 offset:34880
	s_waitcnt lgkmcnt(7)
	v_mfma_f32_16x16x32_bf16 v[36:39], v[100:103], v[72:75], v[36:39]
	ds_read_b128 v[100:103], v191 offset:34880
	s_waitcnt lgkmcnt(7)
	v_mfma_f32_16x16x32_bf16 v[56:59], v[104:107], v[72:75], v[56:59]
	ds_read_b128 v[104:107], v83 offset:44032
	s_waitcnt lgkmcnt(7)
	v_mfma_f32_16x16x32_bf16 v[52:55], v[194:197], v[72:75], v[52:55]
	ds_read_b128 v[194:197], v84 offset:46336
	s_waitcnt lgkmcnt(7)
	v_mfma_f32_16x16x32_bf16 v[44:47], v[198:201], v[72:75], v[44:47]
	ds_read_b128 v[198:201], v85 offset:48640
	s_waitcnt lgkmcnt(7)
	v_mfma_f32_16x16x32_bf16 v[48:51], v[232:235], v[72:75], v[48:51]
	ds_read_b128 v[232:235], v86 offset:50944
	s_waitcnt lgkmcnt(7)
	v_mfma_f32_16x16x32_bf16 v[28:31], v[88:91], v[68:71], v[28:31]
	s_waitcnt lgkmcnt(6)
	v_mfma_f32_16x16x32_bf16 v[40:43], v[92:95], v[68:71], v[40:43]
	s_waitcnt lgkmcnt(5)
	v_mfma_f32_16x16x32_bf16 v[32:35], v[96:99], v[68:71], v[32:35]
	s_waitcnt lgkmcnt(4)
	v_mfma_f32_16x16x32_bf16 v[36:39], v[100:103], v[68:71], v[36:39]
	s_waitcnt lgkmcnt(3)
	v_mfma_f32_16x16x32_bf16 v[56:59], v[104:107], v[68:71], v[56:59]
	s_waitcnt lgkmcnt(2)
	v_mfma_f32_16x16x32_bf16 v[52:55], v[194:197], v[68:71], v[52:55]
	s_waitcnt lgkmcnt(1)
	v_mfma_f32_16x16x32_bf16 v[44:47], v[198:201], v[68:71], v[44:47]
	s_waitcnt lgkmcnt(0)
	v_mfma_f32_16x16x32_bf16 v[48:51], v[232:235], v[68:71], v[48:51]
	s_waitcnt vmcnt(19)
	v_mov_b64_e32 v[74:75], v[66:67]
	v_mov_b64_e32 v[70:71], v[62:63]
	v_mov_b64_e32 v[72:73], v[64:65]
	v_mov_b64_e32 v[68:69], v[60:61]
	s_cbranch_scc0 .LBB0_1135

; __device__ __forceinline__ int otid() { int t = threadIdx.x; asm volatile("" : "+v"(t)); return t; }
; __device__ NOINL void norm_mod_bf_phase(const bf16_t* xb, int nrows, const float* g, const float* mod  , int si, bf16_t* hb) {
;     const int tid = otid(), w = tid >> 6, lane = tid & 63;
;     const int stride = gridDim.x * 8;
;     for (int row = blockIdx.x * 8 + w; row < nrows; row += 2 * stride) {
;         u32x4 q[2][2]; int rows[2] = {row, row + stride};
; #pragma unroll
;         for (int u = 0; u < 2; ++u)
;             if (rows[u] < nrows) {
; #pragma unroll
;                 for (int j = 0; j < 2; ++j) q[u][j] = *(const u32x4*)(xb + (size_t)rows[u] * DM + 8 * lane + 512 * j);
.LBB0_1630:
	s_lshl_b32 s6, s0, 10
	s_lshl_b64 s[0:1], s[6:7], 2
	v_readlane_b32 s4, v252, 22
	v_mov_b32_e32 v0, v202
	s_waitcnt lgkmcnt(0)
	s_add_u32 s40, s4, s0
	v_readlane_b32 s0, v254, 9
	v_ashrrev_i32_e32 v2, 6, v0
	v_readlane_b32 s5, v252, 23
	v_add_u32_e32 v36, s0, v2
	s_addc_u32 s41, s5, s1
	v_cmp_gt_i32_e32 vcc, s87, v36
	s_and_saveexec_b64 s[46:47], vcc
	s_cbranch_execz .LBB0_1637
	v_cmp_lt_i32_e32 vcc, v210, v204
	v_lshlrev_b32_e32 v0, 3, v0
	v_and_b32_e32 v2, 0x1f8, v0
	v_cndmask_b32_e32 v3, v203, v210, vcc
	v_cmp_lt_i32_e32 vcc, v209, v204
	v_readlane_b32 s20, v252, 43
	v_lshlrev_b32_e32 v0, 1, v2
	v_cndmask_b32_e32 v8, v203, v209, vcc
	v_cmp_lt_i32_e32 vcc, v208, v204
	v_lshlrev_b32_e32 v38, 2, v8
	v_readlane_b32 s21, v252, 44
	v_cndmask_b32_e32 v8, v203, v208, vcc
	v_cmp_lt_i32_e32 vcc, v207, v204
	v_lshlrev_b32_e32 v39, 2, v8
	v_readlane_b32 s22, v252, 45
	v_cndmask_b32_e32 v8, v203, v207, vcc
	v_cmp_lt_i32_e32 vcc, v206, v204
	v_lshlrev_b32_e32 v40, 2, v8
	v_readlane_b32 s23, v252, 46
	v_cndmask_b32_e32 v8, v203, v206, vcc
	v_cmp_lt_i32_e32 vcc, v205, v204
	v_lshlrev_b32_e32 v41, 2, v8
	v_lshl_add_u64 v[24:25], s[20:21], 0, v[0:1]
	v_cndmask_b32_e32 v8, v203, v205, vcc
	v_readlane_b32 s0, v255, 30
	v_lshlrev_b32_e32 v42, 2, v8
	v_lshlrev_b32_e32 v8, 2, v2
	v_mov_b32_e32 v9, v1
	v_readlane_b32 s20, v254, 16
	v_readlane_b32 s1, v255, 31
	s_add_u32 s48, s0, 0x3000
	v_lshl_add_u64 v[26:27], s[40:41], 0, v[8:9]
	v_or_b32_e32 v8, 0x200, v2
	v_readlane_b32 s22, v254, 18
	v_readlane_b32 s23, v254, 19
	s_addc_u32 s49, s1, 0
	v_lshlrev_b32_e32 v3, 2, v3
	v_lshl_add_u64 v[28:29], s[22:23], 0, v[0:1]
	s_mov_b64 s[54:55], 0
	v_lshlrev_b32_e32 v30, 2, v8
	v_readlane_b32 s21, v254, 17
	v_mov_b32_e32 v104, v36
	v_ashrrev_i32_e32 v105, 31, v104
	v_lshlrev_b64 v[104:105], 11, v[104:105]
	v_lshl_add_u64 v[104:105], v[24:25], 0, v[104:105]
	global_load_dwordx4 v[96:99], v[104:105], off
	global_load_dwordx4 v[100:103], v[104:105], off offset:1024
	s_branch .LBB0_1633

; __device__ __forceinline__ unsigned pk2(float lo, float hi) { const f32v2_t f = {lo, hi}; const bf16v2_t b = __builtin_convertvector(f, bf16v2_t); return __builtin_bit_cast(unsigned, b); }
; __device__ NOINL void norm_mod_bf_phase(const bf16_t* xb, int nrows, const float* g, const float* mod  , int si, bf16_t* hb) {
;     ...
;     for (int row = blockIdx.x * 8 + w; row < nrows; row += 2 * stride) {
;         u32x4 q[2][2]; int rows[2] = {row, row + stride};
; #pragma unroll
;         for (int u = 0; u < 2; ++u)
;             if (rows[u] < nrows) {
; #pragma unroll
;                 for (int j = 0; j < 2; ++j) q[u][j] = *(const u32x4*)(xb + (size_t)rows[u] * DM + 8 * lane + 512 * j);
;             }
; #pragma unroll
;         for (int u = 0; u < 2; ++u)
;             if (rows[u] < nrows) {
;                 float v[2][8]; float ss = 0.f;
; #pragma unroll
;                 for (int j = 0; j < 2; ++j) { unpack8(q[u][j], v[j]);
; #pragma unroll
;                     for (int e = 0; e < 8; ++e) ss += v[j][e] * v[j][e]; }
;                 const float inv = rsqrtf(wave_sum(ss) * (1.f / DM) + 1e-6f);
;                 const float* sh = mod + (size_t)(rows[u] >> 11) * 6144 + si * 1024; const float* scp = sh + 1024;
; #pragma unroll
;                 for (int j = 0; j < 2; ++j) {
;                     const int c = 8 * lane + 512 * j;
;                     float o[8];
; #pragma unroll
;                     for (int h4 = 0; h4 < 2; ++h4) {
;                         const f32x4 gv = *(const f32x4*)(g + c + 4 * h4), sv = *(const f32x4*)(scp + c + 4 * h4), hv = *(const f32x4*)(sh + c + 4 * h4);
; #pragma unroll
;                         for (int e = 0; e < 4; ++e) o[4 * h4 + e] = v[j][4 * h4 + e] * inv * gv[e] * (1.f + sv[e]) + hv[e];
;                     }
;                     u32x4 pk; pk.x = pk2(o[0], o[1]); pk.y = pk2(o[2], o[3]); pk.z = pk2(o[4], o[5]); pk.w = pk2(o[6], o[7]);
;                     *(u32x4*)(hb + (size_t)rows[u] * DM + c) = pk;
;                 }
.LBB0_1633:
	v_ashrrev_i32_e32 v37, 31, v36
	v_lshlrev_b64 v[34:35], 11, v[36:37]
	v_lshl_add_u64 v[16:17], v[24:25], 0, v[34:35]
	v_add_u32_e32 v32, s11, v36
	v_cmp_gt_i32_e32 vcc, s87, v32
	v_ashrrev_i32_e32 v33, 31, v32
	s_and_saveexec_b64 s[44:45], vcc
	s_cbranch_execz .LBB0_1635
	v_lshlrev_b64 v[8:9], 11, v[32:33]
	v_lshl_add_u64 v[8:9], v[24:25], 0, v[8:9]
	global_load_dwordx4 v[12:15], v[8:9], off
	s_nop 0
	global_load_dwordx4 v[8:11], v[8:9], off offset:1024
.LBB0_1635:
	s_or_b64 exec, exec, s[44:45]
	v_ashrrev_i32_e32 v0, 11, v36
	v_mul_hi_i32_i24_e32 v37, 0x6000, v0
	v_mul_i32_i24_e32 v36, 0x6000, v0
	v_lshl_add_u64 v[36:37], s[48:49], 0, v[36:37]
	s_mov_b64 s[0:1], 0x1000
	v_lshl_add_u64 v[68:69], v[36:37], 0, s[0:1]
	v_lshlrev_b32_e32 v0, 2, v2
	v_lshl_add_u64 v[56:57], v[68:69], 0, v[0:1]
	v_lshl_add_u64 v[70:71], v[36:37], 0, v[0:1]
	global_load_dwordx4 v[44:47], v[26:27], off offset:16
	global_load_dwordx4 v[48:51], v[26:27], off
	global_load_dwordx4 v[52:55], v[56:57], off offset:16
	s_nop 0
	global_load_dwordx4 v[56:59], v[56:57], off
	s_nop 0
	global_load_dwordx4 v[60:63], v[70:71], off offset:16
	global_load_dwordx4 v[64:67], v[70:71], off
	v_mov_b32_e32 v167, v1
	v_mov_b32_e32 v166, v30
	v_lshl_add_u64 v[168:169], v[68:69], 0, v[166:167]
	global_load_dwordx4 v[170:173], v[26:27], off offset:2048
	global_load_dwordx4 v[174:177], v[168:169], off
	global_load_dwordx4 v[178:181], v[26:27], off offset:2064
	global_load_dwordx4 v[186:189], v[168:169], off offset:16
	global_load_dwordx4 v[166:169], v[70:71], off offset:2048
	global_load_dwordx4 v[190:193], v[70:71], off offset:2064
	s_waitcnt vmcnt(6)
	v_mov_b32_e32 v20, v96
	v_mov_b32_e32 v21, v97
	v_mov_b32_e32 v22, v98
	v_mov_b32_e32 v23, v99
	v_mov_b32_e32 v16, v100
	v_mov_b32_e32 v17, v101
	v_mov_b32_e32 v18, v102
	v_mov_b32_e32 v19, v103
	v_lshlrev_b32_e32 v80, 16, v20
	v_and_b32_e32 v81, 0xffff0000, v20
	v_lshlrev_b32_e32 v76, 16, v21
	v_and_b32_e32 v77, 0xffff0000, v21
	v_pk_mul_f32 v[20:21], v[80:81], v[80:81]
	v_pk_mul_f32 v[78:79], v[76:77], v[76:77]
	v_add_f32_e32 v20, v20, v21
	v_lshlrev_b32_e32 v74, 16, v22
	v_and_b32_e32 v75, 0xffff0000, v22
	v_add_f32_e32 v20, v78, v20
	v_lshlrev_b32_e32 v36, 16, v23
	v_and_b32_e32 v37, 0xffff0000, v23
	v_pk_mul_f32 v[22:23], v[74:75], v[74:75]
	v_add_f32_e32 v20, v79, v20
	v_add_f32_e32 v20, v22, v20
	v_pk_mul_f32 v[72:73], v[36:37], v[36:37]
	v_add_f32_e32 v20, v23, v20
	v_lshlrev_b32_e32 v92, 16, v16
	v_and_b32_e32 v93, 0xffff0000, v16
	v_add_f32_e32 v20, v72, v20
	v_lshlrev_b32_e32 v88, 16, v17
	v_and_b32_e32 v89, 0xffff0000, v17
	v_pk_mul_f32 v[16:17], v[92:93], v[92:93]
	v_add_f32_e32 v20, v73, v20
	v_add_f32_e32 v16, v16, v20
	v_pk_mul_f32 v[90:91], v[88:89], v[88:89]
	v_add_f32_e32 v16, v17, v16
	v_lshlrev_b32_e32 v86, 16, v18
	v_and_b32_e32 v87, 0xffff0000, v18
	v_add_f32_e32 v16, v90, v16
	v_lshlrev_b32_e32 v82, 16, v19
	v_and_b32_e32 v83, 0xffff0000, v19
	v_pk_mul_f32 v[18:19], v[86:87], v[86:87]
	v_add_f32_e32 v16, v91, v16
	v_add_f32_e32 v16, v18, v16
	v_pk_mul_f32 v[84:85], v[82:83], v[82:83]
	v_add_f32_e32 v16, v19, v16
	v_add_f32_e32 v16, v84, v16
	v_add_f32_e32 v16, v85, v16
	ds_bpermute_b32 v17, v3, v16
	v_lshl_add_u64 v[72:73], v[28:29], 0, v[34:35]
	s_waitcnt lgkmcnt(0)
	v_add_f32_e32 v16, v16, v17
	ds_bpermute_b32 v17, v38, v16
	s_waitcnt lgkmcnt(0)
	v_add_f32_e32 v16, v16, v17
	ds_bpermute_b32 v17, v39, v16
	s_waitcnt lgkmcnt(0)
	v_add_f32_e32 v16, v16, v17
	ds_bpermute_b32 v17, v40, v16
	s_waitcnt lgkmcnt(0)
	v_add_f32_e32 v16, v16, v17
	ds_bpermute_b32 v17, v41, v16
	s_waitcnt lgkmcnt(0)
	v_add_f32_e32 v16, v16, v17
	ds_bpermute_b32 v17, v42, v16
	s_waitcnt lgkmcnt(0)
	v_add_f32_e32 v16, v16, v17
	v_fmamk_f32 v16, v16, 0x3a800000, v211
	v_mul_f32_e32 v17, 0x4b800000, v16
	v_cmp_gt_f32_e64 s[44:45], s79, v16
	v_pk_add_f32 v[22:23], v[52:53], 1.0 op_sel_hi:[1,0]
	v_pk_add_f32 v[34:35], v[58:59], 1.0 op_sel_hi:[1,0]
	v_cndmask_b32_e64 v16, v16, v17, s[44:45]
	v_rsq_f32_e32 v16, v16
	s_nop 0
	v_mul_f32_e32 v17, 0x45800000, v16
	v_cndmask_b32_e64 v78, v16, v17, s[44:45]
	v_pk_mul_f32 v[20:21], v[78:79], v[74:75] op_sel_hi:[0,1]
	v_pk_mul_f32 v[20:21], v[44:45], v[20:21]
	v_pk_mul_f32 v[16:17], v[78:79], v[80:81] op_sel_hi:[0,1]
	v_pk_mul_f32 v[18:19], v[78:79], v[76:77] op_sel_hi:[0,1]
	v_pk_fma_f32 v[20:21], v[22:23], v[20:21], v[60:61]
	v_pk_mul_f32 v[22:23], v[78:79], v[36:37] op_sel_hi:[0,1]
	v_pk_mul_f32 v[16:17], v[48:49], v[16:17]
	v_pk_mul_f32 v[18:19], v[50:51], v[18:19]
	v_pk_add_f32 v[44:45], v[56:57], 1.0 op_sel_hi:[1,0]
	v_pk_add_f32 v[48:49], v[54:55], 1.0 op_sel_hi:[1,0]
	v_pk_mul_f32 v[22:23], v[46:47], v[22:23]
	v_pk_fma_f32 v[16:17], v[44:45], v[16:17], v[64:65]
	v_pk_fma_f32 v[18:19], v[34:35], v[18:19], v[66:67]
	v_pk_fma_f32 v[22:23], v[48:49], v[22:23], v[62:63]
	v_cvt_pk_bf16_f32 v16, v16, v17
	v_cvt_pk_bf16_f32 v17, v18, v19
	v_cvt_pk_bf16_f32 v18, v20, v21
	v_cvt_pk_bf16_f32 v19, v22, v23
	global_store_dwordx4 v[72:73], v[16:19], off
	s_nop 0
	v_pk_mul_f32 v[56:57], v[78:79], v[92:93] op_sel_hi:[0,1]
	v_pk_mul_f32 v[58:59], v[78:79], v[88:89] op_sel_hi:[0,1]
	v_pk_mul_f32 v[60:61], v[78:79], v[86:87] op_sel_hi:[0,1]
	v_pk_mul_f32 v[62:63], v[78:79], v[82:83] op_sel_hi:[0,1]
	s_waitcnt vmcnt(6)
	v_pk_mul_f32 v[16:17], v[170:171], v[56:57]
	s_waitcnt vmcnt(5)
	v_pk_add_f32 v[20:21], v[174:175], 1.0 op_sel_hi:[1,0]
	v_pk_mul_f32 v[18:19], v[172:173], v[58:59]
	v_pk_add_f32 v[22:23], v[176:177], 1.0 op_sel_hi:[1,0]
	s_waitcnt vmcnt(4)
	v_pk_mul_f32 v[34:35], v[60:61], v[178:179]
	s_waitcnt vmcnt(3)
	v_pk_add_f32 v[44:45], v[186:187], 1.0 op_sel_hi:[1,0]
	v_pk_mul_f32 v[36:37], v[62:63], v[180:181]
	v_pk_add_f32 v[46:47], v[188:189], 1.0 op_sel_hi:[1,0]
	s_waitcnt vmcnt(2)
	v_pk_fma_f32 v[16:17], v[20:21], v[16:17], v[166:167]
	v_pk_fma_f32 v[18:19], v[22:23], v[18:19], v[168:169]
	s_waitcnt vmcnt(1)
	v_pk_fma_f32 v[20:21], v[34:35], v[44:45], v[190:191]
	v_pk_fma_f32 v[22:23], v[36:37], v[46:47], v[192:193]
	v_cvt_pk_bf16_f32 v16, v16, v17
	v_cvt_pk_bf16_f32 v17, v18, v19
	v_cvt_pk_bf16_f32 v18, v20, v21
	v_cvt_pk_bf16_f32 v19, v22, v23
	global_store_dwordx4 v[72:73], v[16:19], off offset:1024
	s_and_saveexec_b64 s[44:45], vcc
	s_cbranch_execz .LBB0_1632
; __device__ __forceinline__ unsigned pk2(float lo, float hi) { const f32v2_t f = {lo, hi}; const bf16v2_t b = __builtin_convertvector(f, bf16v2_t); return __builtin_bit_cast(unsigned, b); }
; __device__ NOINL void norm_mod_bf_phase(const bf16_t* xb, int nrows, const float* g, const float* mod  , int si, bf16_t* hb) {
;     ...
;     for (int row = blockIdx.x * 8 + w; row < nrows; row += 2 * stride) {
;         u32x4 q[2][2]; int rows[2] = {row, row + stride};
; #pragma unroll
;         for (int u = 0; u < 2; ++u)
;             if (rows[u] < nrows) {
; #pragma unroll
;                 for (int j = 0; j < 2; ++j) q[u][j] = *(const u32x4*)(xb + (size_t)rows[u] * DM + 8 * lane + 512 * j);
;             }
; #pragma unroll
;         for (int u = 0; u < 2; ++u)
;             if (rows[u] < nrows) {
;                 float v[2][8]; float ss = 0.f;
; #pragma unroll
;                 for (int j = 0; j < 2; ++j) { unpack8(q[u][j], v[j]);
; #pragma unroll
;                     for (int e = 0; e < 8; ++e) ss += v[j][e] * v[j][e]; }
;                 const float inv = rsqrtf(wave_sum(ss) * (1.f / DM) + 1e-6f);
;                 const float* sh = mod + (size_t)(rows[u] >> 11) * 6144 + si * 1024; const float* scp = sh + 1024;
; #pragma unroll
;                 for (int j = 0; j < 2; ++j) {
;                     const int c = 8 * lane + 512 * j;
;                     float o[8];
; #pragma unroll
;                     for (int h4 = 0; h4 < 2; ++h4) {
;                         const f32x4 gv = *(const f32x4*)(g + c + 4 * h4), sv = *(const f32x4*)(scp + c + 4 * h4), hv = *(const f32x4*)(sh + c + 4 * h4);
; #pragma unroll
;                         for (int e = 0; e < 4; ++e) o[4 * h4 + e] = v[j][4 * h4 + e] * inv * gv[e] * (1.f + sv[e]) + hv[e];
;                     }
;                     u32x4 pk; pk.x = pk2(o[0], o[1]); pk.y = pk2(o[2], o[3]); pk.z = pk2(o[4], o[5]); pk.w = pk2(o[6], o[7]);
;                     *(u32x4*)(hb + (size_t)rows[u] * DM + c) = pk;
;                 }
	v_ashrrev_i32_e32 v16, 11, v32
	v_mul_hi_i32_i24_e32 v17, 0x6000, v16
	v_mul_i32_i24_e32 v16, 0x6000, v16
	v_lshl_add_u64 v[16:17], s[48:49], 0, v[16:17]
	v_lshl_add_u64 v[56:57], v[16:17], 0, s[0:1]
	v_lshl_add_u64 v[44:45], v[56:57], 0, v[0:1]
	v_lshl_add_u64 v[58:59], v[16:17], 0, v[0:1]
	global_load_dwordx4 v[166:169], v[26:27], off offset:16
	global_load_dwordx4 v[170:173], v[26:27], off
	global_load_dwordx4 v[174:177], v[44:45], off offset:16
	global_load_dwordx4 v[178:181], v[44:45], off
	global_load_dwordx4 v[186:189], v[58:59], off offset:16
	global_load_dwordx4 v[190:193], v[58:59], off
	v_mov_b32_e32 v31, v1
	v_lshl_add_u64 v[182:183], v[56:57], 0, v[30:31]
	global_load_dwordx4 v[194:197], v[26:27], off offset:2048
	global_load_dwordx4 v[198:201], v[182:183], off
	global_load_dwordx4 v[234:237], v[26:27], off offset:2064
	global_load_dwordx4 v[238:241], v[182:183], off offset:16
	global_load_dwordx4 v[242:245], v[58:59], off offset:2048
	global_load_dwordx4 v[246:249], v[58:59], off offset:2064
	s_nop 0
	s_nop 0
	v_add_u32_e32 v104, s11, v32
	v_ashrrev_i32_e32 v105, 31, v104
	v_lshlrev_b64 v[104:105], 11, v[104:105]
	v_lshl_add_u64 v[104:105], v[24:25], 0, v[104:105]
	global_load_dwordx4 v[96:99], v[104:105], off
	global_load_dwordx4 v[100:103], v[104:105], off offset:1024
	v_lshlrev_b32_e32 v72, 16, v12
	v_and_b32_e32 v73, 0xffff0000, v12
	v_lshlrev_b32_e32 v68, 16, v13
	v_and_b32_e32 v69, 0xffff0000, v13
	v_pk_mul_f32 v[74:75], v[72:73], v[72:73]
	v_pk_mul_f32 v[70:71], v[68:69], v[68:69]
	v_add_f32_e32 v0, v74, v75
	v_lshlrev_b32_e32 v64, 16, v14
	v_and_b32_e32 v65, 0xffff0000, v14
	v_add_f32_e32 v0, v70, v0
	v_pk_mul_f32 v[66:67], v[64:65], v[64:65]
	v_add_f32_e32 v0, v71, v0
	v_lshlrev_b32_e32 v60, 16, v15
	v_and_b32_e32 v61, 0xffff0000, v15
	v_add_f32_e32 v0, v66, v0
	v_pk_mul_f32 v[62:63], v[60:61], v[60:61]
	v_add_f32_e32 v0, v67, v0
	v_lshlrev_b32_e32 v88, 16, v8
	v_and_b32_e32 v89, 0xffff0000, v8
	v_add_f32_e32 v0, v62, v0
	v_pk_mul_f32 v[90:91], v[88:89], v[88:89]
	v_add_f32_e32 v0, v63, v0
	v_lshlrev_b32_e32 v84, 16, v9
	v_and_b32_e32 v85, 0xffff0000, v9
	v_add_f32_e32 v0, v90, v0
	v_pk_mul_f32 v[86:87], v[84:85], v[84:85]
	v_add_f32_e32 v0, v91, v0
	v_lshlrev_b32_e32 v80, 16, v10
	v_and_b32_e32 v81, 0xffff0000, v10
	v_add_f32_e32 v0, v86, v0
	v_pk_mul_f32 v[82:83], v[80:81], v[80:81]
	v_add_f32_e32 v0, v87, v0
	v_lshlrev_b32_e32 v76, 16, v11
	v_and_b32_e32 v77, 0xffff0000, v11
	v_add_f32_e32 v0, v82, v0
	v_pk_mul_f32 v[78:79], v[76:77], v[76:77]
	v_add_f32_e32 v0, v83, v0
	v_add_f32_e32 v0, v78, v0
	v_add_f32_e32 v0, v79, v0
	ds_bpermute_b32 v43, v3, v0
	v_lshlrev_b64 v[62:63], 11, v[32:33]
	v_lshl_add_u64 v[62:63], v[28:29], 0, v[62:63]
	s_waitcnt lgkmcnt(0)
	v_add_f32_e32 v0, v0, v43
	ds_bpermute_b32 v43, v38, v0
	s_waitcnt lgkmcnt(0)
	v_add_f32_e32 v0, v0, v43
	ds_bpermute_b32 v43, v39, v0
	s_waitcnt lgkmcnt(0)
	v_add_f32_e32 v0, v0, v43
	ds_bpermute_b32 v43, v40, v0
	s_waitcnt lgkmcnt(0)
	v_add_f32_e32 v0, v0, v43
	ds_bpermute_b32 v43, v41, v0
	s_waitcnt lgkmcnt(0)
	v_add_f32_e32 v0, v0, v43
	ds_bpermute_b32 v43, v42, v0
	s_waitcnt lgkmcnt(0)
	v_add_f32_e32 v0, v0, v43
	v_fmamk_f32 v0, v0, 0x3a800000, v211
	v_mul_f32_e32 v43, 0x4b800000, v0
	v_cmp_gt_f32_e32 vcc, s79, v0
	s_waitcnt vmcnt(11)
	v_pk_add_f32 v[34:35], v[174:175], 1.0 op_sel_hi:[1,0]
	s_waitcnt vmcnt(10)
	v_pk_add_f32 v[46:47], v[180:181], 1.0 op_sel_hi:[1,0]
	v_cndmask_b32_e32 v0, v0, v43, vcc
	v_rsq_f32_e32 v0, v0
	v_pk_add_f32 v[44:45], v[178:179], 1.0 op_sel_hi:[1,0]
	v_pk_add_f32 v[36:37], v[176:177], 1.0 op_sel_hi:[1,0]
	v_mul_f32_e32 v31, 0x45800000, v0
	v_cndmask_b32_e32 v0, v0, v31, vcc
	v_pk_mul_f32 v[64:65], v[0:1], v[64:65] op_sel_hi:[0,1]
	v_pk_mul_f32 v[16:17], v[166:167], v[64:65]
	v_pk_mul_f32 v[66:67], v[0:1], v[72:73] op_sel_hi:[0,1]
	v_pk_mul_f32 v[68:69], v[0:1], v[68:69] op_sel_hi:[0,1]
	s_waitcnt vmcnt(9)
	v_pk_fma_f32 v[34:35], v[34:35], v[16:17], v[186:187]
	v_pk_mul_f32 v[16:17], v[0:1], v[60:61] op_sel_hi:[0,1]
	v_pk_mul_f32 v[20:21], v[170:171], v[66:67]
	v_pk_mul_f32 v[22:23], v[172:173], v[68:69]
	v_pk_mul_f32 v[16:17], v[168:169], v[16:17]
	s_waitcnt vmcnt(8)
	v_pk_fma_f32 v[20:21], v[44:45], v[20:21], v[190:191]
	v_pk_fma_f32 v[22:23], v[46:47], v[22:23], v[192:193]
	v_pk_fma_f32 v[36:37], v[36:37], v[16:17], v[188:189]
	v_cvt_pk_bf16_f32 v16, v20, v21
	v_cvt_pk_bf16_f32 v17, v22, v23
	v_cvt_pk_bf16_f32 v18, v34, v35
	v_cvt_pk_bf16_f32 v19, v36, v37
	global_store_dwordx4 v[62:63], v[16:19], off
	s_nop 0
	v_pk_mul_f32 v[56:57], v[0:1], v[88:89] op_sel_hi:[0,1]
	v_pk_mul_f32 v[58:59], v[0:1], v[84:85] op_sel_hi:[0,1]
	v_pk_mul_f32 v[60:61], v[0:1], v[80:81] op_sel_hi:[0,1]
	v_pk_mul_f32 v[64:65], v[0:1], v[76:77] op_sel_hi:[0,1]
	s_waitcnt vmcnt(8)
	v_pk_mul_f32 v[16:17], v[194:195], v[56:57]
	s_waitcnt vmcnt(7)
	v_pk_add_f32 v[20:21], v[198:199], 1.0 op_sel_hi:[1,0]
	v_pk_mul_f32 v[18:19], v[196:197], v[58:59]
	v_pk_add_f32 v[22:23], v[200:201], 1.0 op_sel_hi:[1,0]
	s_waitcnt vmcnt(6)
	v_pk_mul_f32 v[34:35], v[60:61], v[234:235]
	s_waitcnt vmcnt(5)
	v_pk_add_f32 v[44:45], v[238:239], 1.0 op_sel_hi:[1,0]
	v_pk_mul_f32 v[36:37], v[64:65], v[236:237]
	v_pk_add_f32 v[46:47], v[240:241], 1.0 op_sel_hi:[1,0]
	s_waitcnt vmcnt(4)
	v_pk_fma_f32 v[16:17], v[20:21], v[16:17], v[242:243]
	v_pk_fma_f32 v[18:19], v[22:23], v[18:19], v[244:245]
	s_waitcnt vmcnt(3)
	v_pk_fma_f32 v[20:21], v[34:35], v[44:45], v[246:247]
	v_pk_fma_f32 v[22:23], v[36:37], v[46:47], v[248:249]
	v_cvt_pk_bf16_f32 v16, v16, v17
	v_cvt_pk_bf16_f32 v17, v18, v19
	v_cvt_pk_bf16_f32 v18, v20, v21
	v_cvt_pk_bf16_f32 v19, v22, v23
	global_store_dwordx4 v[62:63], v[16:19], off offset:1024
	s_branch .LBB0_1632
